# rwkv_apply loader: nt cache hint on the LDS-DMA loads of the once-read chunk operands
# speedup vs baseline: 1.0277x; 1.0006x over previous
.Lld_wdone:
	s_lshl_b32 s15, s3, 6
	v_add_u32_e32 v6, s15, v146
	v_lshrrev_b32_e32 v7, 3, v6
	v_and_b32_e32 v6, 7, v6
	v_lshlrev_b32_e32 v3, 7, v7
	v_lshl_add_u32 v3, v6, 4, v3
	v_lshlrev_b32_e32 v5, 11, v7
	v_lshl_add_u32 v5, v6, 4, v5
	s_lshr_b32 s15, s2, 4
	s_lshl_b32 s15, s15, 23
	s_and_b32 s20, s2, 15
	s_lshl_b32 s20, s20, 7
	s_add_u32 s15, s15, s20
	s_add_u32 s68, s52, s15
	s_addc_u32 s69, s53, 0
	s_add_u32 s68, s68, 0x7ff8000
	s_addc_u32 s69, s69, 0
	s_cmp_ge_u32 s3, 2
	s_cselect_b32 s72, -1, 0
	s_cselect_b32 s73, -1, 0
	s_mov_b32 s15, 0
	s_and_b32 s22, s15, 3
	s_mul_i32 s22, s22, 29952
	s_lshl_b32 s20, s15, 1
	s_mul_i32 s23, s20, 0x3200
	s_add_u32 s28, s4, s23
	s_addc_u32 s29, s5, 0
	s_mul_i32 s23, s20, s8
	s_add_u32 s64, s6, s23
	s_addc_u32 s65, s7, 0
	s_add_u32 s26, s22, s10
	s_mov_b32 m0, s26
	s_nop 0
	global_load_lds_dwordx4 v0, s[28:29] nt
	s_add_u32 s28, s28, 0x1000
	s_addc_u32 s29, s29, 0
	s_add_i32 m0, s26, 0x1000
	s_nop 0
	global_load_lds_dwordx4 v0, s[28:29] nt
	s_add_u32 s28, s28, 0x1000
	s_addc_u32 s29, s29, 0
	s_add_i32 m0, s26, 0x2000
	s_nop 0
	global_load_lds_dwordx4 v0, s[28:29] nt
	s_add_i32 m0, s22, s9
	s_mov_b64 exec, s[12:13]
	global_load_lds_dwordx4 v1, s[64:65] nt
	s_mov_b64 exec, -1
	s_add_u32 s20, s20, 1
	s_add_u32 s22, s22, 14976
	s_mul_i32 s23, s20, 0x3200
	s_add_u32 s28, s4, s23
	s_addc_u32 s29, s5, 0
	s_mul_i32 s23, s20, s8
	s_add_u32 s64, s6, s23
	s_addc_u32 s65, s7, 0
	s_add_u32 s26, s22, s10
	s_mov_b32 m0, s26
	s_nop 0
	global_load_lds_dwordx4 v0, s[28:29] nt
	s_add_u32 s28, s28, 0x1000
	s_addc_u32 s29, s29, 0
	s_add_i32 m0, s26, 0x1000
	s_nop 0
	global_load_lds_dwordx4 v0, s[28:29] nt
	s_add_u32 s28, s28, 0x1000
	s_addc_u32 s29, s29, 0
	s_add_i32 m0, s26, 0x2000
	s_nop 0
	global_load_lds_dwordx4 v0, s[28:29] nt
	s_add_i32 m0, s22, s9
	s_mov_b64 exec, s[12:13]
	global_load_lds_dwordx4 v1, s[64:65] nt
	s_mov_b64 exec, -1
	s_mov_b32 s15, 1
	s_and_b32 s22, s15, 3
	s_mul_i32 s22, s22, 29952
	s_lshl_b32 s20, s15, 1
	s_mul_i32 s23, s20, 0x3200
	s_add_u32 s28, s4, s23
	s_addc_u32 s29, s5, 0
	s_mul_i32 s23, s20, s8
	s_add_u32 s64, s6, s23
	s_addc_u32 s65, s7, 0
	s_add_u32 s26, s22, s10
	s_mov_b32 m0, s26
	s_nop 0
	global_load_lds_dwordx4 v0, s[28:29] nt
	s_add_u32 s28, s28, 0x1000
	s_addc_u32 s29, s29, 0
	s_add_i32 m0, s26, 0x1000
	s_nop 0
	global_load_lds_dwordx4 v0, s[28:29] nt
	s_add_u32 s28, s28, 0x1000
	s_addc_u32 s29, s29, 0
	s_add_i32 m0, s26, 0x2000
	s_nop 0
	global_load_lds_dwordx4 v0, s[28:29] nt
	s_add_i32 m0, s22, s9
	s_mov_b64 exec, s[12:13]
	global_load_lds_dwordx4 v1, s[64:65] nt
	s_mov_b64 exec, -1
	s_add_u32 s20, s20, 1
	s_add_u32 s22, s22, 14976
	s_mul_i32 s23, s20, 0x3200
	s_add_u32 s28, s4, s23
	s_addc_u32 s29, s5, 0
	s_mul_i32 s23, s20, s8
	s_add_u32 s64, s6, s23
	s_addc_u32 s65, s7, 0
	s_add_u32 s26, s22, s10
	s_mov_b32 m0, s26
	s_nop 0
	global_load_lds_dwordx4 v0, s[28:29] nt
	s_add_u32 s28, s28, 0x1000
	s_addc_u32 s29, s29, 0
	s_add_i32 m0, s26, 0x1000
	s_nop 0
	global_load_lds_dwordx4 v0, s[28:29] nt
	s_add_u32 s28, s28, 0x1000
	s_addc_u32 s29, s29, 0
	s_add_i32 m0, s26, 0x2000
	s_nop 0
	global_load_lds_dwordx4 v0, s[28:29] nt
	s_add_i32 m0, s22, s9
	s_mov_b64 exec, s[12:13]
	global_load_lds_dwordx4 v1, s[64:65] nt
	s_mov_b64 exec, -1
	s_mov_b32 s15, 2
	s_and_b32 s22, s15, 3
	s_mul_i32 s22, s22, 29952
	s_lshl_b32 s20, s15, 1
	s_mul_i32 s23, s20, 0x3200
	s_add_u32 s28, s4, s23
	s_addc_u32 s29, s5, 0
	s_mul_i32 s23, s20, s8
	s_add_u32 s64, s6, s23
	s_addc_u32 s65, s7, 0
	s_add_u32 s26, s22, s10
	s_mov_b32 m0, s26
	s_nop 0
	global_load_lds_dwordx4 v0, s[28:29] nt
	s_add_u32 s28, s28, 0x1000
	s_addc_u32 s29, s29, 0
	s_add_i32 m0, s26, 0x1000
	s_nop 0
	global_load_lds_dwordx4 v0, s[28:29] nt
	s_add_u32 s28, s28, 0x1000
	s_addc_u32 s29, s29, 0
	s_add_i32 m0, s26, 0x2000
	s_nop 0
	global_load_lds_dwordx4 v0, s[28:29] nt
	s_add_i32 m0, s22, s9
	s_mov_b64 exec, s[12:13]
	global_load_lds_dwordx4 v1, s[64:65] nt
	s_mov_b64 exec, -1
	s_add_u32 s20, s20, 1
	s_add_u32 s22, s22, 14976
	s_mul_i32 s23, s20, 0x3200
	s_add_u32 s28, s4, s23
	s_addc_u32 s29, s5, 0
	s_mul_i32 s23, s20, s8
	s_add_u32 s64, s6, s23
	s_addc_u32 s65, s7, 0
	s_add_u32 s26, s22, s10
	s_mov_b32 m0, s26
	s_nop 0
	global_load_lds_dwordx4 v0, s[28:29] nt
	s_add_u32 s28, s28, 0x1000
	s_addc_u32 s29, s29, 0
	s_add_i32 m0, s26, 0x1000
	s_nop 0
	global_load_lds_dwordx4 v0, s[28:29] nt
	s_add_u32 s28, s28, 0x1000
	s_addc_u32 s29, s29, 0
	s_add_i32 m0, s26, 0x2000
	s_nop 0
	global_load_lds_dwordx4 v0, s[28:29] nt
	s_add_i32 m0, s22, s9
	s_mov_b64 exec, s[12:13]
	global_load_lds_dwordx4 v1, s[64:65] nt
	s_mov_b64 exec, -1
	s_waitcnt vmcnt(16)
	s_barrier
	s_mov_b32 s14, 0
.Lld_loop:
	s_add_u32 s15, s14, 3
	s_cmp_gt_u32 s15, 127
	s_cbranch_scc1 .Lld_tail
	s_and_b32 s22, s15, 3
	s_mul_i32 s22, s22, 29952
	s_lshl_b32 s20, s15, 1
	s_mul_i32 s23, s20, 0x3200
	s_add_u32 s28, s4, s23
	s_addc_u32 s29, s5, 0
	s_mul_i32 s23, s20, s8
	s_add_u32 s64, s6, s23
	s_addc_u32 s65, s7, 0
	s_add_u32 s26, s22, s10
	s_mov_b32 m0, s26
	s_nop 0
	global_load_lds_dwordx4 v0, s[28:29] nt
	s_add_u32 s28, s28, 0x1000
	s_addc_u32 s29, s29, 0
	s_add_i32 m0, s26, 0x1000
	s_nop 0
	global_load_lds_dwordx4 v0, s[28:29] nt
	s_add_u32 s28, s28, 0x1000
	s_addc_u32 s29, s29, 0
	s_add_i32 m0, s26, 0x2000
	s_nop 0
	global_load_lds_dwordx4 v0, s[28:29] nt
	s_add_i32 m0, s22, s9
	s_mov_b64 exec, s[12:13]
	global_load_lds_dwordx4 v1, s[64:65] nt
	s_mov_b64 exec, -1
	s_add_u32 s20, s20, 1
	s_add_u32 s22, s22, 14976
	s_mul_i32 s23, s20, 0x3200
	s_add_u32 s28, s4, s23
	s_addc_u32 s29, s5, 0
	s_mul_i32 s23, s20, s8
	s_add_u32 s64, s6, s23
	s_addc_u32 s65, s7, 0
	s_add_u32 s26, s22, s10
	s_mov_b32 m0, s26
	s_nop 0
	global_load_lds_dwordx4 v0, s[28:29] nt
	s_add_u32 s28, s28, 0x1000
	s_addc_u32 s29, s29, 0
	s_add_i32 m0, s26, 0x1000
	s_nop 0
	global_load_lds_dwordx4 v0, s[28:29] nt
	s_add_u32 s28, s28, 0x1000
	s_addc_u32 s29, s29, 0
	s_add_i32 m0, s26, 0x2000
	s_nop 0
	global_load_lds_dwordx4 v0, s[28:29] nt
	s_add_i32 m0, s22, s9
	s_mov_b64 exec, s[12:13]
	global_load_lds_dwordx4 v1, s[64:65] nt
	s_mov_b64 exec, -1
	s_waitcnt vmcnt(16)
	s_branch .Lld_bar
